# loop-head placement (guide 9.3): the five 8-phase GEMM K-loops, the attention tile loop and the mix GEMM-unit K-loop heads aligned to 64 bytes
# speedup vs baseline: 1.0030x; 1.0015x over previous
.LBB0_427:
	s_ashr_i32 s21, s20, 31
	s_lshl_b64 s[44:45], s[20:21], 19
	s_add_u32 s70, s52, s44
	s_addc_u32 s71, s53, s45
	s_ashr_i32 s15, s14, 31
	s_lshl_b64 s[44:45], s[14:15], 19
	s_add_u32 s72, s19, s44
	v_mov_b32_e32 v125, 0
	s_addc_u32 s73, s68, s45
	s_andn2_b64 vcc, exec, s[10:11]
	v_mov_b32_e32 v124, v125
	v_mov_b32_e32 v123, v125
	v_mov_b32_e32 v122, v125
	v_mov_b32_e32 v129, v125
	v_mov_b32_e32 v128, v125
	v_mov_b32_e32 v127, v125
	v_mov_b32_e32 v126, v125
	v_mov_b32_e32 v121, v125
	v_mov_b32_e32 v120, v125
	v_mov_b32_e32 v119, v125
	v_mov_b32_e32 v118, v125
	v_mov_b32_e32 v117, v125
	v_mov_b32_e32 v116, v125
	v_mov_b32_e32 v115, v125
	v_mov_b32_e32 v114, v125
	v_mov_b32_e32 v113, v125
	v_mov_b32_e32 v112, v125
	v_mov_b32_e32 v111, v125
	v_mov_b32_e32 v110, v125
	v_mov_b32_e32 v109, v125
	v_mov_b32_e32 v108, v125
	v_mov_b32_e32 v107, v125
	v_mov_b32_e32 v106, v125
	v_mov_b32_e32 v105, v125
	v_mov_b32_e32 v104, v125
	v_mov_b32_e32 v103, v125
	v_mov_b32_e32 v102, v125
	v_mov_b32_e32 v101, v125
	v_mov_b32_e32 v100, v125
	v_mov_b32_e32 v99, v125
	v_mov_b32_e32 v98, v125
	v_mov_b32_e32 v65, v125
	v_mov_b32_e32 v64, v125
	v_mov_b32_e32 v63, v125
	v_mov_b32_e32 v62, v125
	v_mov_b32_e32 v61, v125
	v_mov_b32_e32 v60, v125
	v_mov_b32_e32 v59, v125
	v_mov_b32_e32 v58, v125
	v_mov_b32_e32 v57, v125
	v_mov_b32_e32 v56, v125
	v_mov_b32_e32 v55, v125
	v_mov_b32_e32 v54, v125
	v_mov_b32_e32 v53, v125
	v_mov_b32_e32 v52, v125
	v_mov_b32_e32 v51, v125
	v_mov_b32_e32 v50, v125
	v_mov_b32_e32 v49, v125
	v_mov_b32_e32 v48, v125
	v_mov_b32_e32 v47, v125
	v_mov_b32_e32 v46, v125
	v_mov_b32_e32 v45, v125
	v_mov_b32_e32 v44, v125
	v_mov_b32_e32 v43, v125
	v_mov_b32_e32 v42, v125
	v_mov_b32_e32 v41, v125
	v_mov_b32_e32 v40, v125
	v_mov_b32_e32 v39, v125
	v_mov_b32_e32 v38, v125
	v_mov_b32_e32 v37, v125
	v_mov_b32_e32 v36, v125
	v_mov_b32_e32 v35, v125
	v_mov_b32_e32 v34, v125
	v_mov_b32_e32 v97, v125
	v_mov_b32_e32 v96, v125
	v_mov_b32_e32 v95, v125
	v_mov_b32_e32 v94, v125
	v_mov_b32_e32 v93, v125
	v_mov_b32_e32 v92, v125
	v_mov_b32_e32 v91, v125
	v_mov_b32_e32 v90, v125
	v_mov_b32_e32 v89, v125
	v_mov_b32_e32 v88, v125
	v_mov_b32_e32 v87, v125
	v_mov_b32_e32 v86, v125
	v_mov_b32_e32 v85, v125
	v_mov_b32_e32 v84, v125
	v_mov_b32_e32 v83, v125
	v_mov_b32_e32 v82, v125
	v_mov_b32_e32 v81, v125
	v_mov_b32_e32 v80, v125
	v_mov_b32_e32 v79, v125
	v_mov_b32_e32 v78, v125
	v_mov_b32_e32 v77, v125
	v_mov_b32_e32 v76, v125
	v_mov_b32_e32 v75, v125
	v_mov_b32_e32 v74, v125
	v_mov_b32_e32 v73, v125
	v_mov_b32_e32 v72, v125
	v_mov_b32_e32 v71, v125
	v_mov_b32_e32 v70, v125
	v_mov_b32_e32 v69, v125
	v_mov_b32_e32 v68, v125
	v_mov_b32_e32 v67, v125
	v_mov_b32_e32 v66, v125
	v_mov_b32_e32 v33, v125
	v_mov_b32_e32 v32, v125
	v_mov_b32_e32 v31, v125
	v_mov_b32_e32 v30, v125
	v_mov_b32_e32 v29, v125
	v_mov_b32_e32 v28, v125
	v_mov_b32_e32 v27, v125
	v_mov_b32_e32 v26, v125
	v_mov_b32_e32 v25, v125
	v_mov_b32_e32 v24, v125
	v_mov_b32_e32 v23, v125
	v_mov_b32_e32 v22, v125
	v_mov_b32_e32 v21, v125
	v_mov_b32_e32 v20, v125
	v_mov_b32_e32 v19, v125
	v_mov_b32_e32 v18, v125
	v_mov_b32_e32 v17, v125
	v_mov_b32_e32 v16, v125
	v_mov_b32_e32 v15, v125
	v_mov_b32_e32 v14, v125
	v_mov_b32_e32 v13, v125
	v_mov_b32_e32 v12, v125
	v_mov_b32_e32 v11, v125
	v_mov_b32_e32 v10, v125
	v_mov_b32_e32 v9, v125
	v_mov_b32_e32 v8, v125
	v_mov_b32_e32 v7, v125
	v_mov_b32_e32 v6, v125
	v_mov_b32_e32 v3, v125
	v_mov_b32_e32 v2, v125
	v_mov_b32_e32 v1, v125
	v_mov_b32_e32 v0, v125
	s_cbranch_vccnz .LBB0_431
	s_and_b64 s[44:45], s[4:5], exec
	s_cselect_b32 s15, s71, s7
	s_cselect_b32 s21, s70, s6
	s_cselect_b32 s44, s73, s9
	s_cselect_b32 s45, s72, s8
	s_add_u32 s6, s6, 0x40080
	s_addc_u32 s7, s7, 0
	s_add_u32 s56, s8, 0x100
	v_mov_b32_e32 v0, 0
	s_addc_u32 s57, s9, 0
	s_mov_b32 s8, 0
	v_mov_b32_e32 v1, v0
	v_mov_b32_e32 v2, v0
	v_mov_b32_e32 v3, v0
	v_mov_b32_e32 v6, v0
	v_mov_b32_e32 v7, v0
	v_mov_b32_e32 v8, v0
	v_mov_b32_e32 v9, v0
	v_mov_b32_e32 v10, v0
	v_mov_b32_e32 v11, v0
	v_mov_b32_e32 v12, v0
	v_mov_b32_e32 v13, v0
	v_mov_b32_e32 v14, v0
	v_mov_b32_e32 v15, v0
	v_mov_b32_e32 v16, v0
	v_mov_b32_e32 v17, v0
	v_mov_b32_e32 v18, v0
	v_mov_b32_e32 v19, v0
	v_mov_b32_e32 v20, v0
	v_mov_b32_e32 v21, v0
	v_mov_b32_e32 v22, v0
	v_mov_b32_e32 v23, v0
	v_mov_b32_e32 v24, v0
	v_mov_b32_e32 v25, v0
	v_mov_b32_e32 v26, v0
	v_mov_b32_e32 v27, v0
	v_mov_b32_e32 v28, v0
	v_mov_b32_e32 v29, v0
	v_mov_b32_e32 v30, v0
	v_mov_b32_e32 v31, v0
	v_mov_b32_e32 v32, v0
	v_mov_b32_e32 v33, v0
	v_mov_b32_e32 v66, v0
	v_mov_b32_e32 v67, v0
	v_mov_b32_e32 v68, v0
	v_mov_b32_e32 v69, v0
	v_mov_b32_e32 v70, v0
	v_mov_b32_e32 v71, v0
	v_mov_b32_e32 v72, v0
	v_mov_b32_e32 v73, v0
	v_mov_b32_e32 v74, v0
	v_mov_b32_e32 v75, v0
	v_mov_b32_e32 v76, v0
	v_mov_b32_e32 v77, v0
	v_mov_b32_e32 v78, v0
	v_mov_b32_e32 v79, v0
	v_mov_b32_e32 v80, v0
	v_mov_b32_e32 v81, v0
	v_mov_b32_e32 v82, v0
	v_mov_b32_e32 v83, v0
	v_mov_b32_e32 v84, v0
	v_mov_b32_e32 v85, v0
	v_mov_b32_e32 v86, v0
	v_mov_b32_e32 v87, v0
	v_mov_b32_e32 v88, v0
	v_mov_b32_e32 v89, v0
	v_mov_b32_e32 v90, v0
	v_mov_b32_e32 v91, v0
	v_mov_b32_e32 v92, v0
	v_mov_b32_e32 v93, v0
	v_mov_b32_e32 v94, v0
	v_mov_b32_e32 v95, v0
	v_mov_b32_e32 v96, v0
	v_mov_b32_e32 v97, v0
	v_mov_b32_e32 v34, v0
	v_mov_b32_e32 v35, v0
	v_mov_b32_e32 v36, v0
	v_mov_b32_e32 v37, v0
	v_mov_b32_e32 v38, v0
	v_mov_b32_e32 v39, v0
	v_mov_b32_e32 v40, v0
	v_mov_b32_e32 v41, v0
	v_mov_b32_e32 v42, v0
	v_mov_b32_e32 v43, v0
	v_mov_b32_e32 v44, v0
	v_mov_b32_e32 v45, v0
	v_mov_b32_e32 v46, v0
	v_mov_b32_e32 v47, v0
	v_mov_b32_e32 v48, v0
	v_mov_b32_e32 v49, v0
	v_mov_b32_e32 v50, v0
	v_mov_b32_e32 v51, v0
	v_mov_b32_e32 v52, v0
	v_mov_b32_e32 v53, v0
	v_mov_b32_e32 v54, v0
	v_mov_b32_e32 v55, v0
	v_mov_b32_e32 v56, v0
	v_mov_b32_e32 v57, v0
	v_mov_b32_e32 v58, v0
	v_mov_b32_e32 v59, v0
	v_mov_b32_e32 v60, v0
	v_mov_b32_e32 v61, v0
	v_mov_b32_e32 v62, v0
	v_mov_b32_e32 v63, v0
	v_mov_b32_e32 v64, v0
	v_mov_b32_e32 v65, v0
	v_mov_b32_e32 v98, v0
	v_mov_b32_e32 v99, v0
	v_mov_b32_e32 v100, v0
	v_mov_b32_e32 v101, v0
	v_mov_b32_e32 v102, v0
	v_mov_b32_e32 v103, v0
	v_mov_b32_e32 v104, v0
	v_mov_b32_e32 v105, v0
	v_mov_b32_e32 v106, v0
	v_mov_b32_e32 v107, v0
	v_mov_b32_e32 v108, v0
	v_mov_b32_e32 v109, v0
	v_mov_b32_e32 v110, v0
	v_mov_b32_e32 v111, v0
	v_mov_b32_e32 v112, v0
	v_mov_b32_e32 v113, v0
	v_mov_b32_e32 v114, v0
	v_mov_b32_e32 v115, v0
	v_mov_b32_e32 v116, v0
	v_mov_b32_e32 v117, v0
	v_mov_b32_e32 v118, v0
	v_mov_b32_e32 v119, v0
	v_mov_b32_e32 v120, v0
	v_mov_b32_e32 v121, v0
	v_mov_b32_e32 v126, v0
	v_mov_b32_e32 v127, v0
	v_mov_b32_e32 v128, v0
	v_mov_b32_e32 v129, v0
	v_mov_b32_e32 v122, v0
	v_mov_b32_e32 v123, v0
	v_mov_b32_e32 v124, v0
	v_mov_b32_e32 v125, v0
	.p2align	6

.LBB0_719:
	s_add_i32 s61, s61, 1
	v_readlane_b32 s12, v254, 21
	s_mul_i32 s12, s61, s12
	s_mov_b32 s22, s65
	s_add_i32 s65, s12, s2
	s_cmp_lt_i32 s65, 64
	s_cselect_b64 s[14:15], -1, 0
	s_and_b64 s[12:13], s[14:15], exec
	s_cselect_b32 s12, s65, s22
	s_ashr_i32 s13, s12, 31
	s_lshl_b64 s[12:13], s[12:13], 19
	s_add_u32 s12, s52, s12
	v_mov_b32_e32 v129, 0
	s_addc_u32 s13, s53, s13
	s_andn2_b64 vcc, exec, s[6:7]
	v_mov_b32_e32 v128, v129
	v_mov_b32_e32 v127, v129
	v_mov_b32_e32 v126, v129
	v_mov_b32_e32 v125, v129
	v_mov_b32_e32 v124, v129
	v_mov_b32_e32 v123, v129
	v_mov_b32_e32 v122, v129
	v_mov_b32_e32 v121, v129
	v_mov_b32_e32 v120, v129
	v_mov_b32_e32 v119, v129
	v_mov_b32_e32 v118, v129
	v_mov_b32_e32 v117, v129
	v_mov_b32_e32 v116, v129
	v_mov_b32_e32 v115, v129
	v_mov_b32_e32 v114, v129
	v_mov_b32_e32 v113, v129
	v_mov_b32_e32 v112, v129
	v_mov_b32_e32 v111, v129
	v_mov_b32_e32 v110, v129
	v_mov_b32_e32 v109, v129
	v_mov_b32_e32 v108, v129
	v_mov_b32_e32 v107, v129
	v_mov_b32_e32 v106, v129
	v_mov_b32_e32 v105, v129
	v_mov_b32_e32 v104, v129
	v_mov_b32_e32 v103, v129
	v_mov_b32_e32 v102, v129
	v_mov_b32_e32 v101, v129
	v_mov_b32_e32 v100, v129
	v_mov_b32_e32 v99, v129
	v_mov_b32_e32 v98, v129
	v_mov_b32_e32 v65, v129
	v_mov_b32_e32 v64, v129
	v_mov_b32_e32 v63, v129
	v_mov_b32_e32 v62, v129
	v_mov_b32_e32 v61, v129
	v_mov_b32_e32 v60, v129
	v_mov_b32_e32 v59, v129
	v_mov_b32_e32 v58, v129
	v_mov_b32_e32 v57, v129
	v_mov_b32_e32 v56, v129
	v_mov_b32_e32 v55, v129
	v_mov_b32_e32 v54, v129
	v_mov_b32_e32 v53, v129
	v_mov_b32_e32 v52, v129
	v_mov_b32_e32 v51, v129
	v_mov_b32_e32 v50, v129
	v_mov_b32_e32 v49, v129
	v_mov_b32_e32 v48, v129
	v_mov_b32_e32 v47, v129
	v_mov_b32_e32 v46, v129
	v_mov_b32_e32 v45, v129
	v_mov_b32_e32 v44, v129
	v_mov_b32_e32 v43, v129
	v_mov_b32_e32 v42, v129
	v_mov_b32_e32 v41, v129
	v_mov_b32_e32 v40, v129
	v_mov_b32_e32 v39, v129
	v_mov_b32_e32 v38, v129
	v_mov_b32_e32 v37, v129
	v_mov_b32_e32 v36, v129
	v_mov_b32_e32 v35, v129
	v_mov_b32_e32 v34, v129
	v_mov_b32_e32 v97, v129
	v_mov_b32_e32 v96, v129
	v_mov_b32_e32 v95, v129
	v_mov_b32_e32 v94, v129
	v_mov_b32_e32 v93, v129
	v_mov_b32_e32 v92, v129
	v_mov_b32_e32 v91, v129
	v_mov_b32_e32 v90, v129
	v_mov_b32_e32 v89, v129
	v_mov_b32_e32 v88, v129
	v_mov_b32_e32 v87, v129
	v_mov_b32_e32 v86, v129
	v_mov_b32_e32 v85, v129
	v_mov_b32_e32 v84, v129
	v_mov_b32_e32 v83, v129
	v_mov_b32_e32 v82, v129
	v_mov_b32_e32 v81, v129
	v_mov_b32_e32 v80, v129
	v_mov_b32_e32 v79, v129
	v_mov_b32_e32 v78, v129
	v_mov_b32_e32 v77, v129
	v_mov_b32_e32 v76, v129
	v_mov_b32_e32 v75, v129
	v_mov_b32_e32 v74, v129
	v_mov_b32_e32 v73, v129
	v_mov_b32_e32 v72, v129
	v_mov_b32_e32 v71, v129
	v_mov_b32_e32 v70, v129
	v_mov_b32_e32 v69, v129
	v_mov_b32_e32 v68, v129
	v_mov_b32_e32 v67, v129
	v_mov_b32_e32 v66, v129
	v_mov_b32_e32 v33, v129
	v_mov_b32_e32 v32, v129
	v_mov_b32_e32 v31, v129
	v_mov_b32_e32 v30, v129
	v_mov_b32_e32 v29, v129
	v_mov_b32_e32 v28, v129
	v_mov_b32_e32 v27, v129
	v_mov_b32_e32 v26, v129
	v_mov_b32_e32 v25, v129
	v_mov_b32_e32 v24, v129
	v_mov_b32_e32 v23, v129
	v_mov_b32_e32 v22, v129
	v_mov_b32_e32 v21, v129
	v_mov_b32_e32 v20, v129
	v_mov_b32_e32 v19, v129
	v_mov_b32_e32 v18, v129
	v_mov_b32_e32 v17, v129
	v_mov_b32_e32 v16, v129
	v_mov_b32_e32 v15, v129
	v_mov_b32_e32 v14, v129
	v_mov_b32_e32 v13, v129
	v_mov_b32_e32 v12, v129
	v_mov_b32_e32 v11, v129
	v_mov_b32_e32 v10, v129
	v_mov_b32_e32 v9, v129
	v_mov_b32_e32 v8, v129
	v_mov_b32_e32 v7, v129
	v_mov_b32_e32 v6, v129
	v_mov_b32_e32 v3, v129
	v_mov_b32_e32 v2, v129
	v_mov_b32_e32 v1, v129
	v_mov_b32_e32 v0, v129
	s_cbranch_vccnz .LBB0_722
	s_and_b64 s[22:23], s[14:15], exec
	s_cselect_b32 s74, s13, s21
	s_cselect_b32 s75, s12, s20
	s_add_u32 s76, s20, 0x100
	s_addc_u32 s77, s21, 0
	s_add_u32 s20, s20, 0x40080
	s_addc_u32 s21, s21, 0
	v_mov_b32_e32 v0, 0
	v_lshl_add_u64 v[148:149], s[20:21], 0, v[144:145]
	v_lshl_add_u64 v[150:151], s[20:21], 0, v[146:147]
	s_mov_b32 s70, 0
	s_mov_b64 s[20:21], 0
	v_mov_b32_e32 v1, v0
	v_mov_b32_e32 v2, v0
	v_mov_b32_e32 v3, v0
	v_mov_b32_e32 v6, v0
	v_mov_b32_e32 v7, v0
	v_mov_b32_e32 v8, v0
	v_mov_b32_e32 v9, v0
	v_mov_b32_e32 v10, v0
	v_mov_b32_e32 v11, v0
	v_mov_b32_e32 v12, v0
	v_mov_b32_e32 v13, v0
	v_mov_b32_e32 v14, v0
	v_mov_b32_e32 v15, v0
	v_mov_b32_e32 v16, v0
	v_mov_b32_e32 v17, v0
	v_mov_b32_e32 v18, v0
	v_mov_b32_e32 v19, v0
	v_mov_b32_e32 v20, v0
	v_mov_b32_e32 v21, v0
	v_mov_b32_e32 v22, v0
	v_mov_b32_e32 v23, v0
	v_mov_b32_e32 v24, v0
	v_mov_b32_e32 v25, v0
	v_mov_b32_e32 v26, v0
	v_mov_b32_e32 v27, v0
	v_mov_b32_e32 v28, v0
	v_mov_b32_e32 v29, v0
	v_mov_b32_e32 v30, v0
	v_mov_b32_e32 v31, v0
	v_mov_b32_e32 v32, v0
	v_mov_b32_e32 v33, v0
	v_mov_b32_e32 v66, v0
	v_mov_b32_e32 v67, v0
	v_mov_b32_e32 v68, v0
	v_mov_b32_e32 v69, v0
	v_mov_b32_e32 v70, v0
	v_mov_b32_e32 v71, v0
	v_mov_b32_e32 v72, v0
	v_mov_b32_e32 v73, v0
	v_mov_b32_e32 v74, v0
	v_mov_b32_e32 v75, v0
	v_mov_b32_e32 v76, v0
	v_mov_b32_e32 v77, v0
	v_mov_b32_e32 v78, v0
	v_mov_b32_e32 v79, v0
	v_mov_b32_e32 v80, v0
	v_mov_b32_e32 v81, v0
	v_mov_b32_e32 v82, v0
	v_mov_b32_e32 v83, v0
	v_mov_b32_e32 v84, v0
	v_mov_b32_e32 v85, v0
	v_mov_b32_e32 v86, v0
	v_mov_b32_e32 v87, v0
	v_mov_b32_e32 v88, v0
	v_mov_b32_e32 v89, v0
	v_mov_b32_e32 v90, v0
	v_mov_b32_e32 v91, v0
	v_mov_b32_e32 v92, v0
	v_mov_b32_e32 v93, v0
	v_mov_b32_e32 v94, v0
	v_mov_b32_e32 v95, v0
	v_mov_b32_e32 v96, v0
	v_mov_b32_e32 v97, v0
	v_mov_b32_e32 v34, v0
	v_mov_b32_e32 v35, v0
	v_mov_b32_e32 v36, v0
	v_mov_b32_e32 v37, v0
	v_mov_b32_e32 v38, v0
	v_mov_b32_e32 v39, v0
	v_mov_b32_e32 v40, v0
	v_mov_b32_e32 v41, v0
	v_mov_b32_e32 v42, v0
	v_mov_b32_e32 v43, v0
	v_mov_b32_e32 v44, v0
	v_mov_b32_e32 v45, v0
	v_mov_b32_e32 v46, v0
	v_mov_b32_e32 v47, v0
	v_mov_b32_e32 v48, v0
	v_mov_b32_e32 v49, v0
	v_mov_b32_e32 v50, v0
	v_mov_b32_e32 v51, v0
	v_mov_b32_e32 v52, v0
	v_mov_b32_e32 v53, v0
	v_mov_b32_e32 v54, v0
	v_mov_b32_e32 v55, v0
	v_mov_b32_e32 v56, v0
	v_mov_b32_e32 v57, v0
	v_mov_b32_e32 v58, v0
	v_mov_b32_e32 v59, v0
	v_mov_b32_e32 v60, v0
	v_mov_b32_e32 v61, v0
	v_mov_b32_e32 v62, v0
	v_mov_b32_e32 v63, v0
	v_mov_b32_e32 v64, v0
	v_mov_b32_e32 v65, v0
	v_mov_b32_e32 v98, v0
	v_mov_b32_e32 v99, v0
	v_mov_b32_e32 v100, v0
	v_mov_b32_e32 v101, v0
	v_mov_b32_e32 v102, v0
	v_mov_b32_e32 v103, v0
	v_mov_b32_e32 v104, v0
	v_mov_b32_e32 v105, v0
	v_mov_b32_e32 v106, v0
	v_mov_b32_e32 v107, v0
	v_mov_b32_e32 v108, v0
	v_mov_b32_e32 v109, v0
	v_mov_b32_e32 v110, v0
	v_mov_b32_e32 v111, v0
	v_mov_b32_e32 v112, v0
	v_mov_b32_e32 v113, v0
	v_mov_b32_e32 v114, v0
	v_mov_b32_e32 v115, v0
	v_mov_b32_e32 v116, v0
	v_mov_b32_e32 v117, v0
	v_mov_b32_e32 v118, v0
	v_mov_b32_e32 v119, v0
	v_mov_b32_e32 v120, v0
	v_mov_b32_e32 v121, v0
	v_mov_b32_e32 v122, v0
	v_mov_b32_e32 v123, v0
	v_mov_b32_e32 v124, v0
	v_mov_b32_e32 v125, v0
	v_mov_b32_e32 v126, v0
	v_mov_b32_e32 v127, v0
	v_mov_b32_e32 v128, v0
	v_mov_b32_e32 v129, v0
	.p2align	6

.LBB0_1075:
	s_cmp_lg_u64 s[0:1], 0
	s_cselect_b64 s[18:19], -1, 0
	v_cndmask_b32_e64 v0, 0, 1, s[18:19]
	v_bfe_u32 v1, v144, 3, 3
	v_readfirstlane_b32 s17, v0
	v_ashrrev_i32_e32 v0, 6, v144
	v_lshl_or_b32 v5, v0, 3, v1
	v_lshrrev_b32_e32 v6, 1, v5
	v_ashrrev_i32_e32 v8, 31, v0
	v_lshlrev_b32_e32 v163, 10, v0
	v_xor_b32_e32 v2, v6, v144
	v_mul_lo_u32 v3, s80, v8
	v_mul_lo_u32 v9, s81, v5
	v_mad_u64_u32 v[0:1], s[18:19], s80, v5, 0
	s_and_b64 s[18:19], s[72:73], exec
	v_add_u32_e32 v7, 32, v163
	v_add3_u32 v1, v1, v3, v9
	v_lshlrev_b32_e32 v2, 4, v2
	v_lshl_add_u64 v[0:1], v[0:1], 1, s[78:79]
	v_and_b32_e32 v2, 0x70, v2
	v_mov_b32_e32 v3, v4
	v_readfirstlane_b32 s18, v7
	v_lshl_add_u64 v[0:1], v[0:1], 0, v[2:3]
	s_mov_b32 m0, s18
	v_mul_lo_u32 v9, s76, v8
	global_load_lds_dwordx4 v[0:1], off
	v_mul_lo_u32 v10, s77, v5
	v_mad_u64_u32 v[0:1], s[18:19], s76, v5, 0
	v_add3_u32 v1, v1, v9, v10
	v_add_u32_e32 v9, 0x8000, v7
	v_lshl_add_u64 v[0:1], v[0:1], 1, s[4:5]
	v_readfirstlane_b32 s18, v9
	v_add_u32_e32 v9, 64, v5
	v_lshl_add_u64 v[0:1], v[0:1], 0, v[2:3]
	s_mov_b32 m0, s18
	v_ashrrev_i32_e32 v11, 31, v9
	global_load_lds_dwordx4 v[0:1], off
	v_mul_lo_u32 v12, s80, v11
	v_mul_lo_u32 v13, s81, v9
	v_mad_u64_u32 v[0:1], s[18:19], s80, v9, 0
	v_add_u32_e32 v10, 0x2000, v7
	v_add3_u32 v1, v1, v12, v13
	v_lshl_add_u64 v[0:1], v[0:1], 1, s[78:79]
	v_readfirstlane_b32 s18, v10
	v_lshl_add_u64 v[0:1], v[0:1], 0, v[2:3]
	s_mov_b32 m0, s18
	v_mul_lo_u32 v10, s76, v11
	global_load_lds_dwordx4 v[0:1], off
	v_mul_lo_u32 v12, s77, v9
	v_mad_u64_u32 v[0:1], s[18:19], s76, v9, 0
	v_add3_u32 v1, v1, v10, v12
	v_add_u32_e32 v10, 0xa000, v7
	v_lshl_add_u64 v[0:1], v[0:1], 1, s[4:5]
	v_readfirstlane_b32 s18, v10
	v_add_u32_e32 v10, 0x80, v5
	v_lshl_add_u64 v[0:1], v[0:1], 0, v[2:3]
	s_mov_b32 m0, s18
	v_ashrrev_i32_e32 v13, 31, v10
	global_load_lds_dwordx4 v[0:1], off
	v_mul_lo_u32 v14, s80, v13
	v_mul_lo_u32 v15, s81, v10
	v_mad_u64_u32 v[0:1], s[18:19], s80, v10, 0
	v_add_u32_e32 v12, 0x4000, v7
	v_add3_u32 v1, v1, v14, v15
	v_lshl_add_u64 v[0:1], v[0:1], 1, s[78:79]
	v_readfirstlane_b32 s18, v12
	v_lshl_add_u64 v[0:1], v[0:1], 0, v[2:3]
	s_mov_b32 m0, s18
	v_mul_lo_u32 v12, s76, v13
	global_load_lds_dwordx4 v[0:1], off
	v_mul_lo_u32 v14, s77, v10
	v_mad_u64_u32 v[0:1], s[18:19], s76, v10, 0
	v_add3_u32 v1, v1, v12, v14
	v_add_u32_e32 v12, 0xc000, v7
	v_lshl_add_u64 v[0:1], v[0:1], 1, s[4:5]
	v_readfirstlane_b32 s18, v12
	v_add_u32_e32 v12, 0xc0, v5
	v_lshl_add_u64 v[0:1], v[0:1], 0, v[2:3]
	s_mov_b32 m0, s18
	v_ashrrev_i32_e32 v15, 31, v12
	global_load_lds_dwordx4 v[0:1], off
	v_mul_lo_u32 v16, s80, v15
	v_mul_lo_u32 v17, s81, v12
	v_mad_u64_u32 v[0:1], s[18:19], s80, v12, 0
	v_add_u32_e32 v14, 0x6000, v7
	v_add3_u32 v1, v1, v16, v17
	v_lshl_add_u64 v[0:1], v[0:1], 1, s[78:79]
	v_readfirstlane_b32 s18, v14
	v_lshl_add_u64 v[0:1], v[0:1], 0, v[2:3]
	s_mov_b32 m0, s18
	v_mul_lo_u32 v14, s76, v15
	global_load_lds_dwordx4 v[0:1], off
	v_mul_lo_u32 v16, s77, v12
	v_mad_u64_u32 v[0:1], s[18:19], s76, v12, 0
	v_add3_u32 v1, v1, v14, v16
	v_lshl_add_u64 v[0:1], v[0:1], 1, s[4:5]
	v_lshl_add_u64 v[0:1], v[0:1], 0, v[2:3]
	v_add_u32_e32 v2, 0xe000, v7
	v_bfe_u32 v3, v144, 1, 3
	v_readfirstlane_b32 s18, v2
	s_mov_b32 m0, s18
	s_cselect_b32 s17, 2, s17
	global_load_lds_dwordx4 v[0:1], off
	v_lshrrev_b32_e32 v0, 5, v144
	v_bitop3_b32 v0, v0, v3, 1 bitop3:0x6c
	s_cmp_eq_u32 s17, 0
	v_bfe_u32 v1, v144, 5, 1
	v_lshlrev_b32_e32 v166, 4, v0
	v_lshlrev_b32_e32 v0, 7, v144
	s_cselect_b64 s[72:73], -1, 0
	s_cmp_lg_u32 s17, 0
	v_and_b32_e32 v159, 0x6f80, v0
	v_bitop3_b32 v0, v1, v3, 2 bitop3:0x36
	s_mov_b32 s23, s69
	s_cselect_b64 s[74:75], -1, 0
	v_lshlrev_b32_e32 v165, 4, v0
	v_bitop3_b32 v0, v1, v3, 4 bitop3:0x36
	s_lshl_b64 s[50:51], s[22:23], 7
	v_lshlrev_b32_e32 v164, 4, v0
	v_bitop3_b32 v0, v1, v3, 6 bitop3:0x36
	s_add_u32 s19, s50, 0x80
	v_and_b32_e32 v161, 31, v144
	v_lshrrev_b32_e32 v2, 1, v144
	s_mov_b32 s18, 0x1ffff80
	v_lshlrev_b32_e32 v162, 4, v0
	s_add_u32 s50, s78, 0x80
	v_bitop3_b32 v0, v6, 7, v144 bitop3:0x48
	v_and_or_b32 v2, v2, s18, v161
	s_ff1_i32_b32 s18, s17
	s_addc_u32 s51, s79, 0
	s_lshl_b32 s17, s80, 1
	v_lshlrev_b32_e32 v0, 4, v0
	v_mov_b32_e32 v1, v4
	v_lshlrev_b32_e32 v158, 7, v2
	v_mad_u64_u32 v[2:3], s[56:57], s17, v5, v[0:1]
	s_lshr_b64 s[56:57], s[80:81], 31
	s_nop 0
	v_mul_lo_u32 v6, s56, v5
	v_mul_lo_u32 v7, s17, v8
	v_add3_u32 v3, v6, v3, v7
	v_lshl_add_u64 v[134:135], s[50:51], 0, v[2:3]
	v_mad_u64_u32 v[2:3], s[60:61], s17, v9, v[0:1]
	v_mul_lo_u32 v6, s56, v9
	v_mul_lo_u32 v7, s17, v11
	v_add3_u32 v3, v6, v3, v7
	v_lshl_add_u64 v[136:137], s[50:51], 0, v[2:3]
	v_mad_u64_u32 v[2:3], s[60:61], s17, v10, v[0:1]
	v_mul_lo_u32 v6, s56, v10
	v_mul_lo_u32 v7, s17, v13
	v_add3_u32 v3, v6, v3, v7
	v_lshl_add_u64 v[146:147], s[50:51], 0, v[2:3]
	v_mad_u64_u32 v[2:3], s[60:61], s17, v12, v[0:1]
	v_mul_lo_u32 v6, s56, v12
	v_mul_lo_u32 v7, s17, v15
	s_add_u32 s4, s4, 0x80
	v_add3_u32 v3, v6, v3, v7
	s_addc_u32 s5, s5, 0
	s_lshl_b32 s17, s76, 1
	v_lshl_add_u64 v[148:149], s[50:51], 0, v[2:3]
	v_mad_u64_u32 v[2:3], s[50:51], s17, v5, v[0:1]
	s_lshr_b64 s[50:51], s[76:77], 31
	s_nop 0
	v_mul_lo_u32 v5, s50, v5
	v_mul_lo_u32 v6, s17, v8
	v_add3_u32 v3, v5, v3, v6
	v_lshl_add_u64 v[150:151], s[4:5], 0, v[2:3]
	v_mad_u64_u32 v[2:3], s[56:57], s17, v9, v[0:1]
	v_mul_lo_u32 v5, s50, v9
	v_mul_lo_u32 v6, s17, v11
	v_add3_u32 v3, v5, v3, v6
	v_lshl_add_u64 v[152:153], s[4:5], 0, v[2:3]
	v_mad_u64_u32 v[2:3], s[56:57], s17, v10, v[0:1]
	v_mul_lo_u32 v5, s50, v10
	v_mul_lo_u32 v6, s17, v13
	v_add3_u32 v3, v5, v3, v6
	v_lshl_add_u64 v[154:155], s[4:5], 0, v[2:3]
	v_mad_u64_u32 v[0:1], s[56:57], s17, v12, v[0:1]
	v_mul_lo_u32 v2, s50, v12
	v_mul_lo_u32 v3, s17, v15
	v_add3_u32 v1, v2, v1, v3
	v_mov_b32_e32 v14, v4
	v_mov_b32_e32 v15, v4
	s_waitcnt vmcnt(0)
	v_lshl_add_u64 v[156:157], s[4:5], 0, v[0:1]
	v_mov_b32_e32 v0, v4
	v_mov_b32_e32 v1, v4
	v_mov_b32_e32 v2, v4
	v_mov_b32_e32 v3, v4
	v_mov_b32_e32 v5, v4
	v_mov_b32_e32 v6, v4
	v_mov_b32_e32 v7, v4
	v_mov_b32_e32 v8, v4
	v_mov_b32_e32 v9, v4
	v_mov_b32_e32 v10, v4
	v_mov_b32_e32 v11, v4
	v_mov_b32_e32 v12, v4
	v_mov_b32_e32 v13, v4
	v_mov_b64_e32 v[116:117], v[14:15]
	v_mov_b64_e32 v[132:133], v[14:15]
	v_mov_b64_e32 v[100:101], v[14:15]
	v_mov_b64_e32 v[84:85], v[14:15]
	v_mov_b64_e32 v[68:69], v[14:15]
	v_mov_b64_e32 v[52:53], v[14:15]
	v_mov_b64_e32 v[36:37], v[14:15]
	v_mov_b64_e32 v[114:115], v[12:13]
	v_mov_b64_e32 v[112:113], v[10:11]
	v_mov_b64_e32 v[110:111], v[8:9]
	v_mov_b64_e32 v[108:109], v[6:7]
	v_mov_b64_e32 v[106:107], v[4:5]
	v_mov_b64_e32 v[104:105], v[2:3]
	v_mov_b64_e32 v[102:103], v[0:1]
	v_mov_b64_e32 v[130:131], v[12:13]
	v_mov_b64_e32 v[128:129], v[10:11]
	v_mov_b64_e32 v[126:127], v[8:9]
	v_mov_b64_e32 v[124:125], v[6:7]
	v_mov_b64_e32 v[122:123], v[4:5]
	v_mov_b64_e32 v[120:121], v[2:3]
	v_mov_b64_e32 v[118:119], v[0:1]
	v_mov_b64_e32 v[98:99], v[12:13]
	v_mov_b64_e32 v[96:97], v[10:11]
	v_mov_b64_e32 v[94:95], v[8:9]
	v_mov_b64_e32 v[92:93], v[6:7]
	v_mov_b64_e32 v[90:91], v[4:5]
	v_mov_b64_e32 v[88:89], v[2:3]
	v_mov_b64_e32 v[86:87], v[0:1]
	v_mov_b64_e32 v[82:83], v[12:13]
	v_mov_b64_e32 v[80:81], v[10:11]
	v_mov_b64_e32 v[78:79], v[8:9]
	v_mov_b64_e32 v[76:77], v[6:7]
	v_mov_b64_e32 v[74:75], v[4:5]
	v_mov_b64_e32 v[72:73], v[2:3]
	v_mov_b64_e32 v[70:71], v[0:1]
	v_mov_b64_e32 v[66:67], v[12:13]
	v_mov_b64_e32 v[64:65], v[10:11]
	v_mov_b64_e32 v[62:63], v[8:9]
	v_mov_b64_e32 v[60:61], v[6:7]
	v_mov_b64_e32 v[58:59], v[4:5]
	v_mov_b64_e32 v[56:57], v[2:3]
	v_mov_b64_e32 v[54:55], v[0:1]
	v_mov_b64_e32 v[50:51], v[12:13]
	v_mov_b64_e32 v[48:49], v[10:11]
	v_mov_b64_e32 v[46:47], v[8:9]
	v_mov_b64_e32 v[44:45], v[6:7]
	v_mov_b64_e32 v[42:43], v[4:5]
	v_mov_b64_e32 v[40:41], v[2:3]
	v_mov_b64_e32 v[38:39], v[0:1]
	v_mov_b64_e32 v[34:35], v[12:13]
	v_mov_b64_e32 v[32:33], v[10:11]
	v_mov_b64_e32 v[30:31], v[8:9]
	v_mov_b64_e32 v[28:29], v[6:7]
	v_mov_b64_e32 v[26:27], v[4:5]
	v_mov_b64_e32 v[24:25], v[2:3]
	v_mov_b64_e32 v[22:23], v[0:1]
	v_mov_b64_e32 v[20:21], v[14:15]
	s_mov_b64 s[70:71], 0
	v_lshrrev_b32_e32 v145, 3, v144
	s_mov_b32 s44, 0
	v_bfe_u32 v160, v144, 6, 2
	v_mov_b64_e32 v[18:19], v[12:13]
	v_mov_b64_e32 v[16:17], v[10:11]
	v_mov_b64_e32 v[14:15], v[8:9]
	v_mov_b64_e32 v[12:13], v[6:7]
	v_mov_b64_e32 v[10:11], v[4:5]
	v_mov_b64_e32 v[8:9], v[2:3]
	v_mov_b64_e32 v[6:7], v[0:1]
	s_mov_b32 s23, 0
	s_movk_i32 s50, 0xc0
	s_waitcnt vmcnt(0) lgkmcnt(0)
	s_barrier
	.p2align	6

.Lgate_pf_skip:
	v_lshl_add_u64 v[130:131], v[130:131], 0, s[96:97]
	s_waitcnt lgkmcnt(0)
	s_barrier
	s_cbranch_scc0 .LBB0_1053
	.p2align	6

.LBB0_1256:
	s_add_i32 s60, s61, 1
	s_lshl_b32 s20, s60, 2
	s_mov_b32 s22, s57
	s_add_i32 s57, s20, s6
	s_cmp_lt_u32 s61, 2
	s_cselect_b64 s[74:75], -1, 0
	s_and_b64 s[20:21], s[74:75], exec
	s_cselect_b32 s20, s8, s8
	s_cselect_b32 s22, s57, s22
	s_ashr_i32 s21, s20, 31
	s_lshl_b64 s[20:21], s[20:21], 19
	s_add_u32 s20, s52, s20
	s_addc_u32 s21, s53, s21
	s_ashr_i32 s23, s22, 31
	s_lshl_b64 s[22:23], s[22:23], 19
	s_add_u32 s22, s80, s22
	v_mov_b32_e32 v129, 0
	s_addc_u32 s23, s81, s23
	s_andn2_b64 vcc, exec, s[12:13]
	v_mov_b32_e32 v128, v129
	v_mov_b32_e32 v127, v129
	v_mov_b32_e32 v126, v129
	v_mov_b32_e32 v125, v129
	v_mov_b32_e32 v124, v129
	v_mov_b32_e32 v123, v129
	v_mov_b32_e32 v122, v129
	v_mov_b32_e32 v121, v129
	v_mov_b32_e32 v120, v129
	v_mov_b32_e32 v119, v129
	v_mov_b32_e32 v118, v129
	v_mov_b32_e32 v117, v129
	v_mov_b32_e32 v116, v129
	v_mov_b32_e32 v115, v129
	v_mov_b32_e32 v114, v129
	v_mov_b32_e32 v113, v129
	v_mov_b32_e32 v112, v129
	v_mov_b32_e32 v111, v129
	v_mov_b32_e32 v110, v129
	v_mov_b32_e32 v109, v129
	v_mov_b32_e32 v108, v129
	v_mov_b32_e32 v107, v129
	v_mov_b32_e32 v106, v129
	v_mov_b32_e32 v105, v129
	v_mov_b32_e32 v104, v129
	v_mov_b32_e32 v103, v129
	v_mov_b32_e32 v102, v129
	v_mov_b32_e32 v101, v129
	v_mov_b32_e32 v100, v129
	v_mov_b32_e32 v99, v129
	v_mov_b32_e32 v98, v129
	v_mov_b32_e32 v65, v129
	v_mov_b32_e32 v64, v129
	v_mov_b32_e32 v63, v129
	v_mov_b32_e32 v62, v129
	v_mov_b32_e32 v61, v129
	v_mov_b32_e32 v60, v129
	v_mov_b32_e32 v59, v129
	v_mov_b32_e32 v58, v129
	v_mov_b32_e32 v57, v129
	v_mov_b32_e32 v56, v129
	v_mov_b32_e32 v55, v129
	v_mov_b32_e32 v54, v129
	v_mov_b32_e32 v53, v129
	v_mov_b32_e32 v52, v129
	v_mov_b32_e32 v51, v129
	v_mov_b32_e32 v50, v129
	v_mov_b32_e32 v49, v129
	v_mov_b32_e32 v48, v129
	v_mov_b32_e32 v47, v129
	v_mov_b32_e32 v46, v129
	v_mov_b32_e32 v45, v129
	v_mov_b32_e32 v44, v129
	v_mov_b32_e32 v43, v129
	v_mov_b32_e32 v42, v129
	v_mov_b32_e32 v41, v129
	v_mov_b32_e32 v40, v129
	v_mov_b32_e32 v39, v129
	v_mov_b32_e32 v38, v129
	v_mov_b32_e32 v37, v129
	v_mov_b32_e32 v36, v129
	v_mov_b32_e32 v35, v129
	v_mov_b32_e32 v34, v129
	v_mov_b32_e32 v97, v129
	v_mov_b32_e32 v96, v129
	v_mov_b32_e32 v95, v129
	v_mov_b32_e32 v94, v129
	v_mov_b32_e32 v93, v129
	v_mov_b32_e32 v92, v129
	v_mov_b32_e32 v91, v129
	v_mov_b32_e32 v90, v129
	v_mov_b32_e32 v89, v129
	v_mov_b32_e32 v88, v129
	v_mov_b32_e32 v87, v129
	v_mov_b32_e32 v86, v129
	v_mov_b32_e32 v85, v129
	v_mov_b32_e32 v84, v129
	v_mov_b32_e32 v83, v129
	v_mov_b32_e32 v82, v129
	v_mov_b32_e32 v81, v129
	v_mov_b32_e32 v80, v129
	v_mov_b32_e32 v79, v129
	v_mov_b32_e32 v78, v129
	v_mov_b32_e32 v77, v129
	v_mov_b32_e32 v76, v129
	v_mov_b32_e32 v75, v129
	v_mov_b32_e32 v74, v129
	v_mov_b32_e32 v73, v129
	v_mov_b32_e32 v72, v129
	v_mov_b32_e32 v71, v129
	v_mov_b32_e32 v70, v129
	v_mov_b32_e32 v69, v129
	v_mov_b32_e32 v68, v129
	v_mov_b32_e32 v67, v129
	v_mov_b32_e32 v66, v129
	v_mov_b32_e32 v33, v129
	v_mov_b32_e32 v32, v129
	v_mov_b32_e32 v31, v129
	v_mov_b32_e32 v30, v129
	v_mov_b32_e32 v29, v129
	v_mov_b32_e32 v28, v129
	v_mov_b32_e32 v27, v129
	v_mov_b32_e32 v26, v129
	v_mov_b32_e32 v25, v129
	v_mov_b32_e32 v24, v129
	v_mov_b32_e32 v23, v129
	v_mov_b32_e32 v22, v129
	v_mov_b32_e32 v21, v129
	v_mov_b32_e32 v20, v129
	v_mov_b32_e32 v19, v129
	v_mov_b32_e32 v18, v129
	v_mov_b32_e32 v17, v129
	v_mov_b32_e32 v16, v129
	v_mov_b32_e32 v15, v129
	v_mov_b32_e32 v14, v129
	v_mov_b32_e32 v13, v129
	v_mov_b32_e32 v12, v129
	v_mov_b32_e32 v11, v129
	v_mov_b32_e32 v10, v129
	v_mov_b32_e32 v9, v129
	v_mov_b32_e32 v8, v129
	v_mov_b32_e32 v7, v129
	v_mov_b32_e32 v6, v129
	v_mov_b32_e32 v3, v129
	v_mov_b32_e32 v2, v129
	v_mov_b32_e32 v1, v129
	v_mov_b32_e32 v0, v129
	s_cbranch_vccnz .LBB0_1259
	s_and_b64 s[74:75], s[74:75], exec
	s_cselect_b32 s76, s21, s71
	s_cselect_b32 s77, s20, s70
	s_cselect_b32 s78, s23, s73
	s_cselect_b32 s79, s22, s72
	s_add_u32 s70, s70, 0x40080
	s_addc_u32 s71, s71, 0
	s_add_u32 s83, s72, 0x100
	v_mov_b32_e32 v0, 0
	s_addc_u32 s84, s73, 0
	s_mov_b32 s72, 0
	v_mov_b32_e32 v1, v0
	v_mov_b32_e32 v2, v0
	v_mov_b32_e32 v3, v0
	v_mov_b32_e32 v6, v0
	v_mov_b32_e32 v7, v0
	v_mov_b32_e32 v8, v0
	v_mov_b32_e32 v9, v0
	v_mov_b32_e32 v10, v0
	v_mov_b32_e32 v11, v0
	v_mov_b32_e32 v12, v0
	v_mov_b32_e32 v13, v0
	v_mov_b32_e32 v14, v0
	v_mov_b32_e32 v15, v0
	v_mov_b32_e32 v16, v0
	v_mov_b32_e32 v17, v0
	v_mov_b32_e32 v18, v0
	v_mov_b32_e32 v19, v0
	v_mov_b32_e32 v20, v0
	v_mov_b32_e32 v21, v0
	v_mov_b32_e32 v22, v0
	v_mov_b32_e32 v23, v0
	v_mov_b32_e32 v24, v0
	v_mov_b32_e32 v25, v0
	v_mov_b32_e32 v26, v0
	v_mov_b32_e32 v27, v0
	v_mov_b32_e32 v28, v0
	v_mov_b32_e32 v29, v0
	v_mov_b32_e32 v30, v0
	v_mov_b32_e32 v31, v0
	v_mov_b32_e32 v32, v0
	v_mov_b32_e32 v33, v0
	v_mov_b32_e32 v66, v0
	v_mov_b32_e32 v67, v0
	v_mov_b32_e32 v68, v0
	v_mov_b32_e32 v69, v0
	v_mov_b32_e32 v70, v0
	v_mov_b32_e32 v71, v0
	v_mov_b32_e32 v72, v0
	v_mov_b32_e32 v73, v0
	v_mov_b32_e32 v74, v0
	v_mov_b32_e32 v75, v0
	v_mov_b32_e32 v76, v0
	v_mov_b32_e32 v77, v0
	v_mov_b32_e32 v78, v0
	v_mov_b32_e32 v79, v0
	v_mov_b32_e32 v80, v0
	v_mov_b32_e32 v81, v0
	v_mov_b32_e32 v82, v0
	v_mov_b32_e32 v83, v0
	v_mov_b32_e32 v84, v0
	v_mov_b32_e32 v85, v0
	v_mov_b32_e32 v86, v0
	v_mov_b32_e32 v87, v0
	v_mov_b32_e32 v88, v0
	v_mov_b32_e32 v89, v0
	v_mov_b32_e32 v90, v0
	v_mov_b32_e32 v91, v0
	v_mov_b32_e32 v92, v0
	v_mov_b32_e32 v93, v0
	v_mov_b32_e32 v94, v0
	v_mov_b32_e32 v95, v0
	v_mov_b32_e32 v96, v0
	v_mov_b32_e32 v97, v0
	v_mov_b32_e32 v34, v0
	v_mov_b32_e32 v35, v0
	v_mov_b32_e32 v36, v0
	v_mov_b32_e32 v37, v0
	v_mov_b32_e32 v38, v0
	v_mov_b32_e32 v39, v0
	v_mov_b32_e32 v40, v0
	v_mov_b32_e32 v41, v0
	v_mov_b32_e32 v42, v0
	v_mov_b32_e32 v43, v0
	v_mov_b32_e32 v44, v0
	v_mov_b32_e32 v45, v0
	v_mov_b32_e32 v46, v0
	v_mov_b32_e32 v47, v0
	v_mov_b32_e32 v48, v0
	v_mov_b32_e32 v49, v0
	v_mov_b32_e32 v50, v0
	v_mov_b32_e32 v51, v0
	v_mov_b32_e32 v52, v0
	v_mov_b32_e32 v53, v0
	v_mov_b32_e32 v54, v0
	v_mov_b32_e32 v55, v0
	v_mov_b32_e32 v56, v0
	v_mov_b32_e32 v57, v0
	v_mov_b32_e32 v58, v0
	v_mov_b32_e32 v59, v0
	v_mov_b32_e32 v60, v0
	v_mov_b32_e32 v61, v0
	v_mov_b32_e32 v62, v0
	v_mov_b32_e32 v63, v0
	v_mov_b32_e32 v64, v0
	v_mov_b32_e32 v65, v0
	v_mov_b32_e32 v98, v0
	v_mov_b32_e32 v99, v0
	v_mov_b32_e32 v100, v0
	v_mov_b32_e32 v101, v0
	v_mov_b32_e32 v102, v0
	v_mov_b32_e32 v103, v0
	v_mov_b32_e32 v104, v0
	v_mov_b32_e32 v105, v0
	v_mov_b32_e32 v106, v0
	v_mov_b32_e32 v107, v0
	v_mov_b32_e32 v108, v0
	v_mov_b32_e32 v109, v0
	v_mov_b32_e32 v110, v0
	v_mov_b32_e32 v111, v0
	v_mov_b32_e32 v112, v0
	v_mov_b32_e32 v113, v0
	v_mov_b32_e32 v114, v0
	v_mov_b32_e32 v115, v0
	v_mov_b32_e32 v116, v0
	v_mov_b32_e32 v117, v0
	v_mov_b32_e32 v118, v0
	v_mov_b32_e32 v119, v0
	v_mov_b32_e32 v120, v0
	v_mov_b32_e32 v121, v0
	v_mov_b32_e32 v122, v0
	v_mov_b32_e32 v123, v0
	v_mov_b32_e32 v124, v0
	v_mov_b32_e32 v125, v0
	v_mov_b32_e32 v126, v0
	v_mov_b32_e32 v127, v0
	v_mov_b32_e32 v128, v0
	v_mov_b32_e32 v129, v0
	.p2align	6

.LBB0_1273:
	s_add_u32 s20, s46, s20
	s_addc_u32 s21, s47, s21
	s_lshl_b32 s74, s9, 1
	s_add_u32 s20, s20, s74
	s_addc_u32 s21, s21, 0
	s_add_u32 s22, s19, s22
	s_addc_u32 s23, s68, s23
	s_add_u32 s22, s22, s74
	s_addc_u32 s23, s23, 0
	s_cmp_eq_u32 s50, 0
	s_cbranch_scc1 .LBB0_1441
	s_and_b64 s[72:73], exec, s[72:73]
	s_cselect_b32 s74, s21, s5
	s_cselect_b32 s75, s20, s4
	s_cselect_b32 s76, s23, s71
	s_cselect_b32 s77, s22, s70
	s_add_i32 s78, s50, -2
	s_add_u32 s4, s4, 0x40080
	s_addc_u32 s5, s5, 0
	s_add_u32 s79, s70, 0x100
	v_mov_b32_e32 v0, 0
	s_addc_u32 s84, s71, 0
	s_mov_b32 s70, 0
	v_mov_b32_e32 v1, v0
	v_mov_b32_e32 v2, v0
	v_mov_b32_e32 v3, v0
	v_mov_b32_e32 v6, v0
	v_mov_b32_e32 v7, v0
	v_mov_b32_e32 v8, v0
	v_mov_b32_e32 v9, v0
	v_mov_b32_e32 v10, v0
	v_mov_b32_e32 v11, v0
	v_mov_b32_e32 v12, v0
	v_mov_b32_e32 v13, v0
	v_mov_b32_e32 v14, v0
	v_mov_b32_e32 v15, v0
	v_mov_b32_e32 v16, v0
	v_mov_b32_e32 v17, v0
	v_mov_b32_e32 v18, v0
	v_mov_b32_e32 v19, v0
	v_mov_b32_e32 v20, v0
	v_mov_b32_e32 v21, v0
	v_mov_b32_e32 v22, v0
	v_mov_b32_e32 v23, v0
	v_mov_b32_e32 v24, v0
	v_mov_b32_e32 v25, v0
	v_mov_b32_e32 v26, v0
	v_mov_b32_e32 v27, v0
	v_mov_b32_e32 v28, v0
	v_mov_b32_e32 v29, v0
	v_mov_b32_e32 v30, v0
	v_mov_b32_e32 v31, v0
	v_mov_b32_e32 v32, v0
	v_mov_b32_e32 v33, v0
	v_mov_b32_e32 v66, v0
	v_mov_b32_e32 v67, v0
	v_mov_b32_e32 v68, v0
	v_mov_b32_e32 v69, v0
	v_mov_b32_e32 v70, v0
	v_mov_b32_e32 v71, v0
	v_mov_b32_e32 v72, v0
	v_mov_b32_e32 v73, v0
	v_mov_b32_e32 v74, v0
	v_mov_b32_e32 v75, v0
	v_mov_b32_e32 v76, v0
	v_mov_b32_e32 v77, v0
	v_mov_b32_e32 v78, v0
	v_mov_b32_e32 v79, v0
	v_mov_b32_e32 v80, v0
	v_mov_b32_e32 v81, v0
	v_mov_b32_e32 v82, v0
	v_mov_b32_e32 v83, v0
	v_mov_b32_e32 v84, v0
	v_mov_b32_e32 v85, v0
	v_mov_b32_e32 v86, v0
	v_mov_b32_e32 v87, v0
	v_mov_b32_e32 v88, v0
	v_mov_b32_e32 v89, v0
	v_mov_b32_e32 v90, v0
	v_mov_b32_e32 v91, v0
	v_mov_b32_e32 v92, v0
	v_mov_b32_e32 v93, v0
	v_mov_b32_e32 v94, v0
	v_mov_b32_e32 v95, v0
	v_mov_b32_e32 v96, v0
	v_mov_b32_e32 v97, v0
	v_mov_b32_e32 v34, v0
	v_mov_b32_e32 v35, v0
	v_mov_b32_e32 v36, v0
	v_mov_b32_e32 v37, v0
	v_mov_b32_e32 v38, v0
	v_mov_b32_e32 v39, v0
	v_mov_b32_e32 v40, v0
	v_mov_b32_e32 v41, v0
	v_mov_b32_e32 v42, v0
	v_mov_b32_e32 v43, v0
	v_mov_b32_e32 v44, v0
	v_mov_b32_e32 v45, v0
	v_mov_b32_e32 v46, v0
	v_mov_b32_e32 v47, v0
	v_mov_b32_e32 v48, v0
	v_mov_b32_e32 v49, v0
	v_mov_b32_e32 v50, v0
	v_mov_b32_e32 v51, v0
	v_mov_b32_e32 v52, v0
	v_mov_b32_e32 v53, v0
	v_mov_b32_e32 v54, v0
	v_mov_b32_e32 v55, v0
	v_mov_b32_e32 v56, v0
	v_mov_b32_e32 v57, v0
	v_mov_b32_e32 v58, v0
	v_mov_b32_e32 v59, v0
	v_mov_b32_e32 v60, v0
	v_mov_b32_e32 v61, v0
	v_mov_b32_e32 v62, v0
	v_mov_b32_e32 v63, v0
	v_mov_b32_e32 v64, v0
	v_mov_b32_e32 v65, v0
	v_mov_b32_e32 v98, v0
	v_mov_b32_e32 v99, v0
	v_mov_b32_e32 v100, v0
	v_mov_b32_e32 v101, v0
	v_mov_b32_e32 v102, v0
	v_mov_b32_e32 v103, v0
	v_mov_b32_e32 v104, v0
	v_mov_b32_e32 v105, v0
	v_mov_b32_e32 v106, v0
	v_mov_b32_e32 v107, v0
	v_mov_b32_e32 v108, v0
	v_mov_b32_e32 v109, v0
	v_mov_b32_e32 v110, v0
	v_mov_b32_e32 v111, v0
	v_mov_b32_e32 v112, v0
	v_mov_b32_e32 v113, v0
	v_mov_b32_e32 v114, v0
	v_mov_b32_e32 v115, v0
	v_mov_b32_e32 v116, v0
	v_mov_b32_e32 v117, v0
	v_mov_b32_e32 v118, v0
	v_mov_b32_e32 v119, v0
	v_mov_b32_e32 v120, v0
	v_mov_b32_e32 v121, v0
	v_mov_b32_e32 v122, v0
	v_mov_b32_e32 v123, v0
	v_mov_b32_e32 v124, v0
	v_mov_b32_e32 v125, v0
	v_mov_b32_e32 v126, v0
	v_mov_b32_e32 v127, v0
	v_mov_b32_e32 v128, v0
	v_mov_b32_e32 v129, v0
	.p2align	6

.LBB0_1506:
	s_ashr_i32 s81, s80, 31
	s_lshl_b64 s[8:9], s[80:81], 19
	s_add_u32 s82, s24, s8
	s_addc_u32 s83, s25, s9
	s_ashr_i32 s79, s78, 31
	s_lshl_b64 s[8:9], s[78:79], 19
	s_add_u32 s84, s35, s8
	v_mov_b32_e32 v129, 0
	s_addc_u32 s85, s50, s9
	s_andn2_b64 vcc, exec, s[74:75]
	v_mov_b32_e32 v128, v129
	v_mov_b32_e32 v127, v129
	v_mov_b32_e32 v126, v129
	v_mov_b32_e32 v125, v129
	v_mov_b32_e32 v124, v129
	v_mov_b32_e32 v123, v129
	v_mov_b32_e32 v122, v129
	v_mov_b32_e32 v121, v129
	v_mov_b32_e32 v120, v129
	v_mov_b32_e32 v119, v129
	v_mov_b32_e32 v118, v129
	v_mov_b32_e32 v117, v129
	v_mov_b32_e32 v116, v129
	v_mov_b32_e32 v115, v129
	v_mov_b32_e32 v114, v129
	v_mov_b32_e32 v113, v129
	v_mov_b32_e32 v112, v129
	v_mov_b32_e32 v111, v129
	v_mov_b32_e32 v110, v129
	v_mov_b32_e32 v109, v129
	v_mov_b32_e32 v108, v129
	v_mov_b32_e32 v107, v129
	v_mov_b32_e32 v106, v129
	v_mov_b32_e32 v105, v129
	v_mov_b32_e32 v104, v129
	v_mov_b32_e32 v103, v129
	v_mov_b32_e32 v102, v129
	v_mov_b32_e32 v101, v129
	v_mov_b32_e32 v100, v129
	v_mov_b32_e32 v99, v129
	v_mov_b32_e32 v98, v129
	v_mov_b32_e32 v65, v129
	v_mov_b32_e32 v64, v129
	v_mov_b32_e32 v63, v129
	v_mov_b32_e32 v62, v129
	v_mov_b32_e32 v61, v129
	v_mov_b32_e32 v60, v129
	v_mov_b32_e32 v59, v129
	v_mov_b32_e32 v58, v129
	v_mov_b32_e32 v57, v129
	v_mov_b32_e32 v56, v129
	v_mov_b32_e32 v55, v129
	v_mov_b32_e32 v54, v129
	v_mov_b32_e32 v53, v129
	v_mov_b32_e32 v52, v129
	v_mov_b32_e32 v51, v129
	v_mov_b32_e32 v50, v129
	v_mov_b32_e32 v49, v129
	v_mov_b32_e32 v48, v129
	v_mov_b32_e32 v47, v129
	v_mov_b32_e32 v46, v129
	v_mov_b32_e32 v45, v129
	v_mov_b32_e32 v44, v129
	v_mov_b32_e32 v43, v129
	v_mov_b32_e32 v42, v129
	v_mov_b32_e32 v41, v129
	v_mov_b32_e32 v40, v129
	v_mov_b32_e32 v39, v129
	v_mov_b32_e32 v38, v129
	v_mov_b32_e32 v37, v129
	v_mov_b32_e32 v36, v129
	v_mov_b32_e32 v35, v129
	v_mov_b32_e32 v34, v129
	v_mov_b32_e32 v97, v129
	v_mov_b32_e32 v96, v129
	v_mov_b32_e32 v95, v129
	v_mov_b32_e32 v94, v129
	v_mov_b32_e32 v93, v129
	v_mov_b32_e32 v92, v129
	v_mov_b32_e32 v91, v129
	v_mov_b32_e32 v90, v129
	v_mov_b32_e32 v89, v129
	v_mov_b32_e32 v88, v129
	v_mov_b32_e32 v87, v129
	v_mov_b32_e32 v86, v129
	v_mov_b32_e32 v85, v129
	v_mov_b32_e32 v84, v129
	v_mov_b32_e32 v83, v129
	v_mov_b32_e32 v82, v129
	v_mov_b32_e32 v81, v129
	v_mov_b32_e32 v80, v129
	v_mov_b32_e32 v79, v129
	v_mov_b32_e32 v78, v129
	v_mov_b32_e32 v77, v129
	v_mov_b32_e32 v76, v129
	v_mov_b32_e32 v75, v129
	v_mov_b32_e32 v74, v129
	v_mov_b32_e32 v73, v129
	v_mov_b32_e32 v72, v129
	v_mov_b32_e32 v71, v129
	v_mov_b32_e32 v70, v129
	v_mov_b32_e32 v69, v129
	v_mov_b32_e32 v68, v129
	v_mov_b32_e32 v67, v129
	v_mov_b32_e32 v66, v129
	v_mov_b32_e32 v33, v129
	v_mov_b32_e32 v32, v129
	v_mov_b32_e32 v31, v129
	v_mov_b32_e32 v30, v129
	v_mov_b32_e32 v29, v129
	v_mov_b32_e32 v28, v129
	v_mov_b32_e32 v27, v129
	v_mov_b32_e32 v26, v129
	v_mov_b32_e32 v25, v129
	v_mov_b32_e32 v24, v129
	v_mov_b32_e32 v23, v129
	v_mov_b32_e32 v22, v129
	v_mov_b32_e32 v21, v129
	v_mov_b32_e32 v20, v129
	v_mov_b32_e32 v19, v129
	v_mov_b32_e32 v18, v129
	v_mov_b32_e32 v17, v129
	v_mov_b32_e32 v16, v129
	v_mov_b32_e32 v15, v129
	v_mov_b32_e32 v14, v129
	v_mov_b32_e32 v13, v129
	v_mov_b32_e32 v12, v129
	v_mov_b32_e32 v11, v129
	v_mov_b32_e32 v10, v129
	v_mov_b32_e32 v9, v129
	v_mov_b32_e32 v8, v129
	v_mov_b32_e32 v7, v129
	v_mov_b32_e32 v6, v129
	v_mov_b32_e32 v3, v129
	v_mov_b32_e32 v2, v129
	v_mov_b32_e32 v1, v129
	v_mov_b32_e32 v0, v129
	s_cbranch_vccnz .LBB0_1509
	s_and_b64 s[8:9], s[4:5], exec
	s_cselect_b32 s12, s83, s1
	s_cselect_b32 s13, s82, s0
	s_cselect_b32 s14, s85, s7
	s_cselect_b32 s15, s84, s6
	s_add_u32 s0, s0, 0x40080
	s_addc_u32 s1, s1, 0
	s_add_u32 s16, s6, 0x100
	v_mov_b32_e32 v0, 0
	s_addc_u32 s17, s7, 0
	s_mov_b32 s6, 0
	v_mov_b32_e32 v1, v0
	v_mov_b32_e32 v2, v0
	v_mov_b32_e32 v3, v0
	v_mov_b32_e32 v6, v0
	v_mov_b32_e32 v7, v0
	v_mov_b32_e32 v8, v0
	v_mov_b32_e32 v9, v0
	v_mov_b32_e32 v10, v0
	v_mov_b32_e32 v11, v0
	v_mov_b32_e32 v12, v0
	v_mov_b32_e32 v13, v0
	v_mov_b32_e32 v14, v0
	v_mov_b32_e32 v15, v0
	v_mov_b32_e32 v16, v0
	v_mov_b32_e32 v17, v0
	v_mov_b32_e32 v18, v0
	v_mov_b32_e32 v19, v0
	v_mov_b32_e32 v20, v0
	v_mov_b32_e32 v21, v0
	v_mov_b32_e32 v22, v0
	v_mov_b32_e32 v23, v0
	v_mov_b32_e32 v24, v0
	v_mov_b32_e32 v25, v0
	v_mov_b32_e32 v26, v0
	v_mov_b32_e32 v27, v0
	v_mov_b32_e32 v28, v0
	v_mov_b32_e32 v29, v0
	v_mov_b32_e32 v30, v0
	v_mov_b32_e32 v31, v0
	v_mov_b32_e32 v32, v0
	v_mov_b32_e32 v33, v0
	v_mov_b32_e32 v66, v0
	v_mov_b32_e32 v67, v0
	v_mov_b32_e32 v68, v0
	v_mov_b32_e32 v69, v0
	v_mov_b32_e32 v70, v0
	v_mov_b32_e32 v71, v0
	v_mov_b32_e32 v72, v0
	v_mov_b32_e32 v73, v0
	v_mov_b32_e32 v74, v0
	v_mov_b32_e32 v75, v0
	v_mov_b32_e32 v76, v0
	v_mov_b32_e32 v77, v0
	v_mov_b32_e32 v78, v0
	v_mov_b32_e32 v79, v0
	v_mov_b32_e32 v80, v0
	v_mov_b32_e32 v81, v0
	v_mov_b32_e32 v82, v0
	v_mov_b32_e32 v83, v0
	v_mov_b32_e32 v84, v0
	v_mov_b32_e32 v85, v0
	v_mov_b32_e32 v86, v0
	v_mov_b32_e32 v87, v0
	v_mov_b32_e32 v88, v0
	v_mov_b32_e32 v89, v0
	v_mov_b32_e32 v90, v0
	v_mov_b32_e32 v91, v0
	v_mov_b32_e32 v92, v0
	v_mov_b32_e32 v93, v0
	v_mov_b32_e32 v94, v0
	v_mov_b32_e32 v95, v0
	v_mov_b32_e32 v96, v0
	v_mov_b32_e32 v97, v0
	v_mov_b32_e32 v34, v0
	v_mov_b32_e32 v35, v0
	v_mov_b32_e32 v36, v0
	v_mov_b32_e32 v37, v0
	v_mov_b32_e32 v38, v0
	v_mov_b32_e32 v39, v0
	v_mov_b32_e32 v40, v0
	v_mov_b32_e32 v41, v0
	v_mov_b32_e32 v42, v0
	v_mov_b32_e32 v43, v0
	v_mov_b32_e32 v44, v0
	v_mov_b32_e32 v45, v0
	v_mov_b32_e32 v46, v0
	v_mov_b32_e32 v47, v0
	v_mov_b32_e32 v48, v0
	v_mov_b32_e32 v49, v0
	v_mov_b32_e32 v50, v0
	v_mov_b32_e32 v51, v0
	v_mov_b32_e32 v52, v0
	v_mov_b32_e32 v53, v0
	v_mov_b32_e32 v54, v0
	v_mov_b32_e32 v55, v0
	v_mov_b32_e32 v56, v0
	v_mov_b32_e32 v57, v0
	v_mov_b32_e32 v58, v0
	v_mov_b32_e32 v59, v0
	v_mov_b32_e32 v60, v0
	v_mov_b32_e32 v61, v0
	v_mov_b32_e32 v62, v0
	v_mov_b32_e32 v63, v0
	v_mov_b32_e32 v64, v0
	v_mov_b32_e32 v65, v0
	v_mov_b32_e32 v98, v0
	v_mov_b32_e32 v99, v0
	v_mov_b32_e32 v100, v0
	v_mov_b32_e32 v101, v0
	v_mov_b32_e32 v102, v0
	v_mov_b32_e32 v103, v0
	v_mov_b32_e32 v104, v0
	v_mov_b32_e32 v105, v0
	v_mov_b32_e32 v106, v0
	v_mov_b32_e32 v107, v0
	v_mov_b32_e32 v108, v0
	v_mov_b32_e32 v109, v0
	v_mov_b32_e32 v110, v0
	v_mov_b32_e32 v111, v0
	v_mov_b32_e32 v112, v0
	v_mov_b32_e32 v113, v0
	v_mov_b32_e32 v114, v0
	v_mov_b32_e32 v115, v0
	v_mov_b32_e32 v116, v0
	v_mov_b32_e32 v117, v0
	v_mov_b32_e32 v118, v0
	v_mov_b32_e32 v119, v0
	v_mov_b32_e32 v120, v0
	v_mov_b32_e32 v121, v0
	v_mov_b32_e32 v122, v0
	v_mov_b32_e32 v123, v0
	v_mov_b32_e32 v124, v0
	v_mov_b32_e32 v125, v0
	v_mov_b32_e32 v126, v0
	v_mov_b32_e32 v127, v0
	v_mov_b32_e32 v128, v0
	v_mov_b32_e32 v129, v0
	.p2align	6
